# attention B far loop: mask applied with v_bfe_i32 + v_bfi_b32 instead of and/cmp/cndmask (no VCC hazards, 16 ands and 18 s_nops fewer per tile)
# baseline (speedup 1.0000x reference)
; template <int DQK, bool MB> ...
;     ...
;                 const unsigned long long mw0 = sm0[kt], mw1 = sm1[kt];
;                 if (pass == 0) {
; #pragma unroll
;                     for (int ks = 0; ks < 4; ++ks) { const unsigned b0 = (unsigned)(mw0 >> (16 * ks + 4 * q)) & 0xFu, b1 = (unsigned)(mw1 >> (16 * ks + 4 * q)) & 0xFu;
; #pragma unroll
;                         for (int j = 0; j < 4; ++j) { s[ks][0][j] = ((b0 >> j) & 1u) ? s[ks][0][j] + tbfar : -INFINITY; s[ks][1][j] = ((b1 >> j) & 1u) ? s[ks][1][j] + tbfar : -INFINITY; } }
.LBB0_665:
	v_lshl_add_u32 v156, s45, 14, v181
	ds_read_b128 v[124:127], v156
	ds_read_b128 v[128:131], v156 offset:1024
	ds_read_b128 v[132:135], v156 offset:2048
	ds_read_b128 v[136:139], v156 offset:3072
	ds_read_b128 v[140:143], v156 offset:4096
	ds_read_b128 v[160:163], v156 offset:5120
	ds_read_b128 v[164:167], v156 offset:6144
	ds_read_b128 v[186:189], v156 offset:7168
	s_waitcnt lgkmcnt(7)
	v_mfma_f32_16x16x32_bf16 v[190:193], v[124:127], v[44:47], 0
	v_mfma_f32_16x16x32_bf16 v[124:127], v[124:127], v[60:63], 0
	s_waitcnt lgkmcnt(6)
	v_mfma_f32_16x16x32_bf16 v[190:193], v[128:131], v[64:67], v[190:193]
	v_mfma_f32_16x16x32_bf16 v[124:127], v[128:131], v[72:75], v[124:127]
	s_waitcnt lgkmcnt(5)
	v_mfma_f32_16x16x32_bf16 v[128:131], v[132:135], v[68:71], v[190:193]
	v_mfma_f32_16x16x32_bf16 v[124:127], v[132:135], v[76:79], v[124:127]
	s_waitcnt lgkmcnt(4)
	v_mfma_f32_16x16x32_bf16 v[128:131], v[136:139], v[80:83], v[128:131]
	v_mfma_f32_16x16x32_bf16 v[124:127], v[136:139], v[56:59], v[124:127]
	ds_read_b128 v[132:135], v156 offset:8192
	ds_read_b128 v[136:139], v156 offset:9216
	ds_read_b128 v[190:193], v156 offset:10240
	ds_read_b128 v[194:197], v156 offset:11264
	s_waitcnt lgkmcnt(7)
	v_mfma_f32_16x16x32_bf16 v[198:201], v[140:143], v[44:47], 0
	v_mfma_f32_16x16x32_bf16 v[140:143], v[140:143], v[60:63], 0
	s_waitcnt lgkmcnt(6)
	v_mfma_f32_16x16x32_bf16 v[198:201], v[160:163], v[64:67], v[198:201]
	v_mfma_f32_16x16x32_bf16 v[140:143], v[160:163], v[72:75], v[140:143]
	s_waitcnt lgkmcnt(5)
	v_mfma_f32_16x16x32_bf16 v[160:163], v[164:167], v[68:71], v[198:201]
	v_mfma_f32_16x16x32_bf16 v[140:143], v[164:167], v[76:79], v[140:143]
	s_waitcnt lgkmcnt(4)
	v_mfma_f32_16x16x32_bf16 v[160:163], v[186:189], v[80:83], v[160:163]
	v_mfma_f32_16x16x32_bf16 v[140:143], v[186:189], v[56:59], v[140:143]
	ds_read_b128 v[164:167], v156 offset:12288
	ds_read_b128 v[186:189], v156 offset:13312
	ds_read_b128 v[198:201], v156 offset:14336
	ds_read_b128 v[202:205], v156 offset:15360
	s_waitcnt lgkmcnt(7)
	v_mfma_f32_16x16x32_bf16 v[206:209], v[132:135], v[44:47], 0
	v_mfma_f32_16x16x32_bf16 v[132:135], v[132:135], v[60:63], 0
	s_waitcnt lgkmcnt(6)
	v_mfma_f32_16x16x32_bf16 v[206:209], v[136:139], v[64:67], v[206:209]
	v_mfma_f32_16x16x32_bf16 v[132:135], v[136:139], v[72:75], v[132:135]
	s_waitcnt lgkmcnt(5)
	v_mfma_f32_16x16x32_bf16 v[136:139], v[190:193], v[68:71], v[206:209]
	v_mfma_f32_16x16x32_bf16 v[132:135], v[190:193], v[76:79], v[132:135]
	s_waitcnt lgkmcnt(4)
	v_mfma_f32_16x16x32_bf16 v[136:139], v[194:197], v[80:83], v[136:139]
	v_mfma_f32_16x16x32_bf16 v[132:135], v[194:197], v[56:59], v[132:135]
	s_waitcnt lgkmcnt(3)
	v_mfma_f32_16x16x32_bf16 v[190:193], v[164:167], v[44:47], 0
	v_mfma_f32_16x16x32_bf16 v[164:167], v[164:167], v[60:63], 0
	s_waitcnt lgkmcnt(2)
	v_mfma_f32_16x16x32_bf16 v[164:167], v[186:189], v[72:75], v[164:167]
	v_mfma_f32_16x16x32_bf16 v[190:193], v[186:189], v[64:67], v[190:193]
	s_waitcnt lgkmcnt(1)
	v_mfma_f32_16x16x32_bf16 v[164:167], v[198:201], v[76:79], v[164:167]
	v_mfma_f32_16x16x32_bf16 v[186:189], v[198:201], v[68:71], v[190:193]
	s_waitcnt lgkmcnt(0)
	v_mfma_f32_16x16x32_bf16 v[164:167], v[202:205], v[56:59], v[164:167]
	v_mfma_f32_16x16x32_bf16 v[186:189], v[202:205], v[80:83], v[186:189]
	v_mov_b32_e32 v156, s4
	s_nop 0
	ds_read2_b64 v[190:193], v156 offset1:32
	s_nop 3
	v_add_f32_e32 v158, v113, v164
	v_add_f32_e32 v164, v113, v165
	v_add_f32_e32 v132, v113, v132
	v_add_f32_e32 v124, v113, v124
	s_waitcnt lgkmcnt(0)
	v_lshrrev_b64 v[156:157], v150, v[192:193]
	v_bfe_i32 v243, v156, 0, 1
	v_add_f32_e32 v126, v113, v126
	v_bfi_b32 v168, v243, v158, v155
	v_bfe_i32 v244, v156, 1, 1
	v_add_f32_e32 v157, v113, v166
	v_bfi_b32 v169, v244, v164, v155
	v_bfe_i32 v245, v156, 2, 1
	v_and_b32_e32 v156, 8, v156
	v_add_f32_e32 v127, v113, v127
	v_bfi_b32 v166, v245, v157, v155
	v_add_f32_e32 v157, v113, v167
	v_bfe_i32 v246, v156, 3, 1
	s_mul_i32 s47, s45, 0x4400
	v_bfi_b32 v185, v246, v157, v155
	v_lshrrev_b64 v[156:157], v150, v[190:191]
	v_add_f32_e32 v157, v113, v186
	v_bfe_i32 v247, v156, 0, 1
	v_and_b32_e32 v165, 4, v156
	v_bfi_b32 v158, v247, v157, v155
	v_add_f32_e32 v157, v113, v187
	v_bfe_i32 v243, v156, 1, 1
	v_and_b32_e32 v156, 8, v156
	v_bfi_b32 v164, v243, v157, v155
	v_add_f32_e32 v157, v113, v188
	v_bfe_i32 v244, v165, 2, 1
	v_bfi_b32 v167, v244, v157, v155
	v_add_f32_e32 v157, v113, v189
	v_bfe_i32 v245, v156, 3, 1
	v_bfi_b32 v183, v245, v157, v155
	v_lshrrev_b64 v[156:157], v152, v[192:193]
	v_bfe_i32 v246, v156, 0, 1
	v_bfi_b32 v186, v246, v132, v155
	v_add_f32_e32 v132, v113, v133
	v_bfe_i32 v247, v156, 1, 1
	v_bfi_b32 v187, v247, v132, v155
	v_add_f32_e32 v132, v113, v134
	v_bfe_i32 v243, v156, 2, 1
	v_bfi_b32 v188, v243, v132, v155
	v_add_f32_e32 v132, v113, v135
	v_bfe_i32 v244, v156, 3, 1
	v_bfi_b32 v189, v244, v132, v155
	v_lshrrev_b64 v[132:133], v152, v[190:191]
	v_add_f32_e32 v133, v113, v136
	v_bfe_i32 v245, v132, 0, 1
	v_bfi_b32 v134, v245, v133, v155
	v_add_f32_e32 v133, v113, v137
	v_bfe_i32 v246, v132, 1, 1
	v_and_b32_e32 v135, 4, v132
	v_and_b32_e32 v132, 8, v132
	v_bfi_b32 v136, v246, v133, v155
	v_add_f32_e32 v133, v113, v138
	v_bfe_i32 v247, v135, 2, 1
	v_lshrrev_b32_e32 v135, v154, v192
	v_and_b32_e32 v135, 1, v135
	v_bfi_b32 v138, v247, v133, v155
	v_add_f32_e32 v133, v113, v139
	v_bfe_i32 v243, v132, 3, 1
	v_bfi_b32 v156, v243, v133, v155
	v_lshrrev_b64 v[132:133], v154, v[192:193]
	v_add_f32_e32 v133, v113, v140
	v_bfe_i32 v244, v135, 0, 1
	v_bfi_b32 v194, v244, v133, v155
	v_add_f32_e32 v133, v113, v141
	v_bfe_i32 v245, v132, 1, 1
	v_and_b32_e32 v135, 4, v132
; template <int DQK, bool MB> ...
;     ...
;                 if (pass == 0) {
; #pragma unroll
;                     for (int ks = 0; ks < 4; ++ks) { const unsigned b0 = (unsigned)(mw0 >> (16 * ks + 4 * q)) & 0xFu, b1 = (unsigned)(mw1 >> (16 * ks + 4 * q)) & 0xFu;
; #pragma unroll
;                         for (int j = 0; j < 4; ++j) { s[ks][0][j] = ((b0 >> j) & 1u) ? s[ks][0][j] + tbfar : -INFINITY; s[ks][1][j] = ((b1 >> j) & 1u) ? s[ks][1][j] + tbfar : -INFINITY; } }
;                 } else
;                 {
;                 float bv[4][2][4];
; #pragma unroll
;                 for (int ks = 0; ks < 4; ++ks) { const i32x4 pk = *(const i32x4*)(posb + 64 * kt + 16 * ks + 4 * q);
; #pragma unroll
;                     for (int j = 0; j < 4; ++j) { const int d0 = min(max(pt0 - pk[j], 0), 128), d1 = min(max(pt1 - pk[j], 0), 128);
;                         bv[ks][0][j] = tb[d0 * 16 + r]; bv[ks][1][j] = tb[d1 * 16 + r]; } }
;                 __builtin_amdgcn_sched_barrier(0);
; #pragma unroll
;                 for (int ks = 0; ks < 4; ++ks) { const unsigned b0 = (unsigned)(mw0 >> (16 * ks + 4 * q)) & 0xFu, b1 = (unsigned)(mw1 >> (16 * ks + 4 * q)) & 0xFu;
; #pragma unroll
;                     for (int j = 0; j < 4; ++j) { s[ks][0][j] = ((b0 >> j) & 1u) ? s[ks][0][j] + bv[ks][0][j] : -INFINITY; s[ks][1][j] = ((b1 >> j) & 1u) ? s[ks][1][j] + bv[ks][1][j] : -INFINITY; } }
;                 }
;             } else if (64 * kt + 63 > wave_qmax - 31) {
; #pragma unroll
;                 for (int ks = 0; ks < 4; ++ks)
; #pragma unroll
;                     for (int j = 0; j < 4; ++j) { const int key = 64 * kt + 16 * ks + 4 * q + j;
;                         s[ks][0][j] = (key <= qi0) ? s[ks][0][j] : -INFINITY; s[ks][1][j] = (key <= qi1) ? s[ks][1][j] : -INFINITY; }
;             }
;             float alpha2[2];
; #pragma unroll
;             for (int ct = 0; ct < 2; ++ct) {
;                 float mx = -INFINITY;
; #pragma unroll
;                 for (int ks = 0; ks < 4; ++ks)
; #pragma unroll
;                     for (int j = 0; j < 4; ++j) mx = fmaxf(mx, s[ks][ct][j]);
;                 mx = fmaxf(mx, __shfl_xor(mx, 16)); mx = fmaxf(mx, __shfl_xor(mx, 32));
;                 const float mnew = fmaxf(mrow[ct], mx), alpha = __builtin_amdgcn_exp2f(mrow[ct] - mnew);
;                 mrow[ct] = mnew;
;                 float ps = 0.f;
; #pragma unroll
	v_and_b32_e32 v132, 8, v132
	v_bfi_b32 v195, v245, v133, v155
	v_add_f32_e32 v133, v113, v142
	v_bfe_i32 v246, v135, 2, 1
	v_lshrrev_b32_e32 v135, v154, v190
	v_and_b32_e32 v135, 1, v135
	v_bfi_b32 v196, v246, v133, v155
	v_add_f32_e32 v133, v113, v143
	v_bfe_i32 v247, v132, 3, 1
	v_bfi_b32 v197, v247, v133, v155
	v_lshrrev_b64 v[132:133], v154, v[190:191]
	v_add_f32_e32 v133, v113, v160
	v_bfe_i32 v243, v135, 0, 1
	v_bfi_b32 v135, v243, v133, v155
	v_add_f32_e32 v133, v113, v161
	v_bfe_i32 v244, v132, 1, 1
	v_and_b32_e32 v137, 4, v132
	v_and_b32_e32 v132, 8, v132
	v_bfi_b32 v140, v244, v133, v155
	v_add_f32_e32 v133, v113, v162
	v_bfe_i32 v245, v137, 2, 1
	v_bfi_b32 v142, v245, v133, v155
	v_add_f32_e32 v133, v113, v163
	v_bfe_i32 v246, v132, 3, 1
	v_bfi_b32 v160, v246, v133, v155
	v_lshrrev_b64 v[132:133], v179, v[192:193]
	v_lshrrev_b32_e32 v133, v179, v192
	v_and_b32_e32 v133, 1, v133
	v_bfe_i32 v247, v133, 0, 1
	v_and_b32_e32 v133, 4, v132
	v_bfi_b32 v162, v247, v124, v155
	v_add_f32_e32 v124, v113, v125
	v_bfe_i32 v243, v132, 1, 1
	v_and_b32_e32 v132, 8, v132
	v_bfi_b32 v192, v243, v124, v155
	v_lshrrev_b64 v[124:125], v179, v[190:191]
	v_add_f32_e32 v125, v113, v128
	v_lshrrev_b32_e32 v128, v179, v190
	v_and_b32_e32 v128, 1, v128
	v_bfe_i32 v244, v128, 0, 1
	v_add_f32_e32 v128, v113, v129
	v_bfi_b32 v125, v244, v125, v155
	v_bfe_i32 v245, v124, 1, 1
	v_add_f32_e32 v129, v113, v130
	v_bfi_b32 v128, v245, v128, v155
	v_bfe_i32 v246, v124, 2, 1
	v_and_b32_e32 v124, 8, v124
	v_add_f32_e32 v130, v113, v131
	v_bfi_b32 v129, v246, v129, v155
	v_bfe_i32 v247, v124, 3, 1
	v_bfi_b32 v124, v247, v130, v155
	v_max3_f32 v130, v125, s79, v128
	v_max3_f32 v130, v130, v129, v124
	v_max3_f32 v130, v130, v135, v140
	v_max3_f32 v130, v130, v142, v160
	v_max3_f32 v130, v130, v134, v136
	v_max3_f32 v130, v130, v138, v156
	v_max3_f32 v130, v130, v158, v164
	v_max3_f32 v130, v130, v167, v183
	ds_bpermute_b32 v131, v159, v130
	v_bfe_i32 v243, v133, 2, 1
	s_waitcnt lgkmcnt(0)
	v_max_f32_e32 v131, v131, v131
	v_max_f32_e32 v130, v130, v131
	ds_bpermute_b32 v131, v184, v130
	v_bfi_b32 v126, v243, v126, v155
	v_bfe_i32 v244, v132, 3, 1
	s_waitcnt lgkmcnt(0)
	v_max3_f32 v182, v123, v130, v131
	v_sub_f32_e32 v241, v182, v123
	v_cmp_lt_f32_e64 s[98:99], 4.0, v241
	s_nop 1
	v_cndmask_b32_e64 v182, v123, v182, s[98:99]
	v_sub_f32_e32 v130, v123, v182
	v_sub_f32_e32 v123, v125, v182
	v_bfi_b32 v132, v244, v127, v155
	v_exp_f32_e32 v157, v123
	v_sub_f32_e32 v123, v128, v182
	v_max3_f32 v128, v162, s79, v192
	v_max3_f32 v128, v128, v126, v132
	v_exp_f32_e32 v143, v123
	v_sub_f32_e32 v123, v129, v182
	v_max3_f32 v128, v128, v194, v195
	v_exp_f32_e32 v141, v123
	v_sub_f32_e32 v123, v124, v182
	v_max3_f32 v128, v128, v196, v197
	v_exp_f32_e32 v139, v123
	v_sub_f32_e32 v123, v135, v182
	v_max3_f32 v128, v128, v186, v187
	v_exp_f32_e32 v137, v123
	v_sub_f32_e32 v123, v140, v182
	v_max3_f32 v128, v128, v188, v189
	v_exp_f32_e32 v135, v123
	v_sub_f32_e32 v123, v142, v182
	v_max3_f32 v128, v128, v168, v169
	v_exp_f32_e32 v133, v123
	v_sub_f32_e32 v123, v160, v182
	v_max3_f32 v128, v128, v166, v185
	v_exp_f32_e32 v131, v123
	v_sub_f32_e32 v123, v134, v182
	ds_bpermute_b32 v134, v159, v128
	v_sub_f32_e32 v124, v158, v182
	v_exp_f32_e32 v165, v124
	v_sub_f32_e32 v124, v164, v182
	v_exp_f32_e32 v161, v124
	s_waitcnt lgkmcnt(0)
	v_max_f32_e32 v134, v134, v134
	v_max_f32_e32 v128, v128, v134
	ds_bpermute_b32 v134, v184, v128
	v_sub_f32_e32 v124, v167, v182
	v_exp_f32_e32 v129, v123
	v_sub_f32_e32 v123, v136, v182
	v_exp_f32_e32 v167, v124
	v_sub_f32_e32 v124, v183, v182
	s_waitcnt lgkmcnt(0)
	v_max3_f32 v183, v122, v128, v134
	v_sub_f32_e32 v242, v183, v122
	v_cmp_lt_f32_e64 s[100:101], 4.0, v242
	s_nop 1
	v_cndmask_b32_e64 v183, v122, v183, s[100:101]
	v_exp_f32_e32 v127, v123
	v_sub_f32_e32 v123, v138, v182
	v_sub_f32_e32 v190, v122, v183
	v_sub_f32_e32 v122, v162, v183
	v_exp_f32_e32 v125, v123
	v_sub_f32_e32 v123, v156, v182
	v_exp_f32_e32 v156, v122
	v_sub_f32_e32 v122, v192, v183
	v_exp_f32_e32 v142, v122
	v_sub_f32_e32 v122, v126, v183
	v_exp_f32_e32 v140, v122
	v_sub_f32_e32 v122, v132, v183
	v_exp_f32_e32 v138, v122
	v_sub_f32_e32 v122, v194, v183
	v_exp_f32_e32 v136, v122
	v_sub_f32_e32 v122, v195, v183
	v_exp_f32_e32 v134, v122
	v_sub_f32_e32 v122, v196, v183
	v_sub_f32_e32 v160, v168, v183
	v_exp_f32_e32 v168, v190
	v_exp_f32_e32 v132, v122
	v_sub_f32_e32 v122, v197, v183
	v_exp_f32_e32 v158, v130
	v_exp_f32_e32 v130, v122
	v_sub_f32_e32 v122, v186, v183
	v_exp_f32_e32 v128, v122
	v_sub_f32_e32 v122, v187, v183
	v_exp_f32_e32 v126, v122
	v_sub_f32_e32 v122, v188, v183
	v_exp_f32_e32 v164, v160
	v_sub_f32_e32 v160, v169, v183
	v_sub_f32_e32 v162, v166, v183
	v_add_u32_e32 v169, s47, v180
	v_exp_f32_e32 v163, v124
	v_exp_f32_e32 v124, v122
	v_sub_f32_e32 v122, v189, v183
	v_exp_f32_e32 v166, v162
	v_sub_f32_e32 v162, v185, v183
	v_add_u32_e32 v185, 0x8000, v169
	v_add_u32_e32 v222, 0x8800, v169
	v_add_u32_e32 v223, 0x9000, v169
	v_add_u32_e32 v225, 0x9800, v169
	v_add_u32_e32 v230, 0xa000, v169
	v_add_u32_e32 v231, 0xa800, v169
	v_add_u32_e32 v232, 0xb000, v169
	v_add_u32_e32 v169, 0xb800, v169
	v_exp_f32_e32 v123, v123
	v_exp_f32_e32 v122, v122
	v_exp_f32_e32 v160, v160
	v_exp_f32_e32 v162, v162
	s_or_b64 s[98:99], s[98:99], s[100:101]
	s_cmp_eq_u64 s[98:99], 0
	s_cbranch_scc1 .Llazy_bf_skip
; template <int DQK, bool MB> ...
;     ...
;             {
; #pragma unroll
;                 for (int ct = 0; ct < 2; ++ct)
; #pragma unroll
;                     for (int dt = 0; dt < 8; ++dt) o[ct][dt] *= alpha2[ct];
;             }
	v_pk_mul_f32 v[30:31], v[30:31], v[168:169] op_sel_hi:[1,0]
	v_pk_mul_f32 v[28:29], v[28:29], v[168:169] op_sel_hi:[1,0]
	v_pk_mul_f32 v[26:27], v[26:27], v[168:169] op_sel_hi:[1,0]
	v_pk_mul_f32 v[24:25], v[24:25], v[168:169] op_sel_hi:[1,0]
	v_pk_mul_f32 v[22:23], v[22:23], v[168:169] op_sel_hi:[1,0]
	v_pk_mul_f32 v[20:21], v[20:21], v[168:169] op_sel_hi:[1,0]
	v_pk_mul_f32 v[18:19], v[18:19], v[168:169] op_sel_hi:[1,0]
	v_pk_mul_f32 v[16:17], v[16:17], v[168:169] op_sel_hi:[1,0]
	v_pk_mul_f32 v[14:15], v[14:15], v[168:169] op_sel_hi:[1,0]
	v_pk_mul_f32 v[12:13], v[12:13], v[168:169] op_sel_hi:[1,0]
	v_pk_mul_f32 v[10:11], v[10:11], v[168:169] op_sel_hi:[1,0]
	v_pk_mul_f32 v[8:9], v[8:9], v[168:169] op_sel_hi:[1,0]
	v_pk_mul_f32 v[6:7], v[6:7], v[168:169] op_sel_hi:[1,0]
	v_pk_mul_f32 v[4:5], v[4:5], v[168:169] op_sel_hi:[1,0]
	v_pk_mul_f32 v[2:3], v[2:3], v[168:169] op_sel_hi:[1,0]
	v_pk_mul_f32 v[0:1], v[0:1], v[168:169] op_sel_hi:[1,0]
	v_pk_mul_f32 v[110:111], v[110:111], v[158:159] op_sel_hi:[1,0]
	v_pk_mul_f32 v[108:109], v[108:109], v[158:159] op_sel_hi:[1,0]
	v_pk_mul_f32 v[106:107], v[106:107], v[158:159] op_sel_hi:[1,0]
	v_pk_mul_f32 v[104:105], v[104:105], v[158:159] op_sel_hi:[1,0]
	v_pk_mul_f32 v[102:103], v[102:103], v[158:159] op_sel_hi:[1,0]
	v_pk_mul_f32 v[100:101], v[100:101], v[158:159] op_sel_hi:[1,0]
	v_pk_mul_f32 v[98:99], v[98:99], v[158:159] op_sel_hi:[1,0]
	v_pk_mul_f32 v[96:97], v[96:97], v[158:159] op_sel_hi:[1,0]
	v_pk_mul_f32 v[86:87], v[86:87], v[158:159] op_sel_hi:[1,0]
	v_pk_mul_f32 v[84:85], v[84:85], v[158:159] op_sel_hi:[1,0]
	v_pk_mul_f32 v[42:43], v[42:43], v[158:159] op_sel_hi:[1,0]
	v_pk_mul_f32 v[40:41], v[40:41], v[158:159] op_sel_hi:[1,0]
	v_pk_mul_f32 v[38:39], v[38:39], v[158:159] op_sel_hi:[1,0]
	v_pk_mul_f32 v[36:37], v[36:37], v[158:159] op_sel_hi:[1,0]
	v_pk_mul_f32 v[34:35], v[34:35], v[158:159] op_sel_hi:[1,0]
	v_pk_mul_f32 v[32:33], v[32:33], v[158:159] op_sel_hi:[1,0]

; __global__ void __launch_bounds__(NTHREADS, 2) fwd_megakernel(Args a) {
	.amdhsa_kernel _Z14fwd_megakernel4Args
		.amdhsa_group_segment_fixed_size 0
		.amdhsa_private_segment_fixed_size 0
		.amdhsa_kernarg_size 408
		.amdhsa_user_sgpr_count 2
		.amdhsa_user_sgpr_dispatch_ptr 0
		.amdhsa_user_sgpr_queue_ptr 0
		.amdhsa_user_sgpr_kernarg_segment_ptr 1
		.amdhsa_user_sgpr_dispatch_id 0
		.amdhsa_user_sgpr_kernarg_preload_length 0
		.amdhsa_user_sgpr_kernarg_preload_offset 0
		.amdhsa_user_sgpr_private_segment_size 0
		.amdhsa_uses_dynamic_stack 0
		.amdhsa_enable_private_segment 0
		.amdhsa_system_sgpr_workgroup_id_x 1
		.amdhsa_system_sgpr_workgroup_id_y 0
		.amdhsa_system_sgpr_workgroup_id_z 0
		.amdhsa_system_sgpr_workgroup_info 0
		.amdhsa_system_vgpr_workitem_id 2
		.amdhsa_next_free_vgpr 248
		.amdhsa_next_free_sgpr 102
		.amdhsa_accum_offset 248
		.amdhsa_reserve_vcc 1
		.amdhsa_float_round_mode_32 0
		.amdhsa_float_round_mode_16_64 0
		.amdhsa_float_denorm_mode_32 3
		.amdhsa_float_denorm_mode_16_64 3
		.amdhsa_dx10_clamp 1
		.amdhsa_ieee_mode 1
		.amdhsa_fp16_overflow 0
		.amdhsa_tg_split 0
		.amdhsa_exception_fp_ieee_invalid_op 0
		.amdhsa_exception_fp_denorm_src 0
		.amdhsa_exception_fp_ieee_div_zero 0
		.amdhsa_exception_fp_ieee_overflow 0
		.amdhsa_exception_fp_ieee_underflow 0
		.amdhsa_exception_fp_ieee_inexact 0
		.amdhsa_exception_int_div_zero 0
	.end_amdhsa_kernel

; __global__ void __launch_bounds__(NTHREADS, 2) fwd_megakernel(Args a) {
amdhsa.kernels:
  - .agpr_count:     0
    .args:
      - .offset:         0
        .size:           152
        .value_kind:     by_value
      - .offset:         152
        .size:           4
        .value_kind:     hidden_block_count_x
      - .offset:         156
        .size:           4
        .value_kind:     hidden_block_count_y
      - .offset:         160
        .size:           4
        .value_kind:     hidden_block_count_z
      - .offset:         164
        .size:           2
        .value_kind:     hidden_group_size_x
      - .offset:         166
        .size:           2
        .value_kind:     hidden_group_size_y
      - .offset:         168
        .size:           2
        .value_kind:     hidden_group_size_z
      - .offset:         170
        .size:           2
        .value_kind:     hidden_remainder_x
      - .offset:         172
        .size:           2
        .value_kind:     hidden_remainder_y
      - .offset:         174
        .size:           2
        .value_kind:     hidden_remainder_z
      - .offset:         192
        .size:           8
        .value_kind:     hidden_global_offset_x
      - .offset:         200
        .size:           8
        .value_kind:     hidden_global_offset_y
      - .offset:         208
        .size:           8
        .value_kind:     hidden_global_offset_z
      - .offset:         216
        .size:           2
        .value_kind:     hidden_grid_dims
      - .offset:         240
        .size:           8
        .value_kind:     hidden_multigrid_sync_arg
      - .offset:         272
        .size:           4
        .value_kind:     hidden_dynamic_lds_size
    .group_segment_fixed_size: 0
    .kernarg_segment_align: 8
    .kernarg_segment_size: 408
    .language:       OpenCL C
    .language_version:
      - 2
      - 0
    .max_flat_workgroup_size: 512
    .name:           _Z14fwd_megakernel4Args
    .private_segment_fixed_size: 0
    .sgpr_count:     108
    .sgpr_spill_count: 3
    .symbol:         _Z14fwd_megakernel4Args.kd
    .uniform_work_group_size: 1
    .uses_dynamic_stack: false
    .vgpr_count:     248
    .vgpr_spill_count: 0
    .wavefront_size: 64
